# relaxed first-iteration K-loop waits extended to the two down GEMMs (P2, P12), rest as comb10
# speedup vs baseline: 1.0055x; 1.0055x over previous
; #define PG8_STAGE(bufoff, gbase, voff) do { _Pragma("unroll") for (int _i = 0; _i < 2; ++_i) \
;         __builtin_amdgcn_global_load_lds((const unsigned*)((const char*)(gbase) + (voff)[_i]), (PG8_LAS unsigned*)(lds + (bufoff) + ldsw + _i * 8192), 16, 0, 0); } while (0)
; #define PG8_LDA(dst, b, h) do { _Pragma("unroll") for (int m = 0; m < 4; ++m) _Pragma("unroll") for (int k = 0; k < 2; ++k) dst[m][k] = *(const PG8_LAS bf16x8*)(lds + PG8_SA(b, h) + aoff + m * 2048 + k * 1024); } while (0)
; #define PG8_LDB(dst, b, h) do { _Pragma("unroll") for (int n = 0; n < 2; ++n) _Pragma("unroll") for (int k = 0; k < 2; ++k) dst[n][k] = *(const PG8_LAS bf16x8*)(lds + PG8_SB(b, h) + boff + n * 2048 + k * 1024); } while (0)
; #define PG8_MMA(ai, bj, At, Bt) do { __builtin_amdgcn_s_setprio(1); _Pragma("unroll") for (int m = 0; m < 4; ++m) _Pragma("unroll") for (int n = 0; n < 2; ++n) _Pragma("unroll") for (int k = 0; k < 2; ++k) \
;         acc[ai][bj][m][n] = __builtin_amdgcn_mfma_f32_16x16x32_bf16(Bt[n][k], At[m][k], acc[ai][bj][m][n], 0, 0, 0); __builtin_amdgcn_s_setprio(0); } while (0)
; #define PG8_WAIT_V(n) asm volatile("s_waitcnt vmcnt(" #n ")" ::: "memory")
; #define PG8_BAR __builtin_amdgcn_s_barrier()
; template <class Epi, class Sched, bool ALIGN_EPI = false, bool SP2 = false>
; __device__ __forceinline__ void gemm_phase(PG8_LAS unsigned char* lds, const Gemm g, const Sched& S, const Epi& E) {
;     ...
;         for (int t = 0; t < nt; t += 2) {
;             const bool last = (t == nt - 2);
;             const char* a1 = cA + (size_t)(t + 1) * kstep;
;             const char* a2 = last ? nA : cA + (size_t)(t + 2) * kstep; const char* b2 = last ? nB : cB + (size_t)(t + 2) * kstep;
;             const char* a3 = a2 + kstep; const char* b3 = b2 + kstep;
;             if (last && has_next) S.a_ready(nxt);
;             if constexpr (SP2) {
;             PG8_LDB(B0, 0, 0); PG8_LDB(B1, 0, 1); PG8_SCHED; PG8_LDA(At, 0, 0); PG8_STAGE(PG8_SA(1, 1), a1 + hstep, voffA);
;             PG8_WAIT_V(8); PG8_WAIT_L(0); PG8_BAR; PG8_MMA(0, 0, At, B0); PG8_MMA(0, 1, At, B1); PG8_BAR; PG8_SCHED;
;     ...
; #pragma unroll
;         for (int a = 0; a < 2; ++a)
; #pragma unroll
;             for (int b = 0; b < 2; ++b)
; #pragma unroll
;                 for (int m = 0; m < 4; ++m)
; #pragma unroll
;                     for (int n = 0; n < 2; ++n) acc[a][b][m][n] = (f32x4){0.f, 0.f, 0.f, 0.f};
.LBB0_369:
	s_add_u32 s22, s22, 0xb0080
	s_addc_u32 s23, s23, 0
	s_add_u32 s46, s24, 0x100
	v_mov_b32_e32 v0, 0
	s_addc_u32 s47, s25, 0
	s_mov_b32 s48, -2
	v_mov_b32_e32 v1, v0
	v_mov_b32_e32 v2, v0
	v_mov_b32_e32 v3, v0
	v_mov_b32_e32 v4, v0
	s_waitcnt lgkmcnt(0)
	v_mov_b32_e32 v5, v0
	v_mov_b32_e32 v6, v0
	v_mov_b32_e32 v7, v0
	v_mov_b32_e32 v16, v0
	v_mov_b32_e32 v17, v0
	v_mov_b32_e32 v18, v0
	v_mov_b32_e32 v19, v0
	v_mov_b32_e32 v20, v0
	v_mov_b32_e32 v21, v0
	v_mov_b32_e32 v22, v0
	v_mov_b32_e32 v23, v0
	v_mov_b32_e32 v32, v0
	v_mov_b32_e32 v33, v0
	v_mov_b32_e32 v34, v0
	v_mov_b32_e32 v35, v0
	v_mov_b32_e32 v36, v0
	v_mov_b32_e32 v37, v0
	v_mov_b32_e32 v38, v0
	v_mov_b32_e32 v39, v0
	v_mov_b32_e32 v48, v0
	v_mov_b32_e32 v49, v0
	v_mov_b32_e32 v50, v0
	v_mov_b32_e32 v51, v0
	v_mov_b32_e32 v52, v0
	v_mov_b32_e32 v53, v0
	v_mov_b32_e32 v54, v0
	v_mov_b32_e32 v55, v0
	v_mov_b32_e32 v8, v0
	v_mov_b32_e32 v9, v0
	v_mov_b32_e32 v10, v0
	v_mov_b32_e32 v11, v0
	v_mov_b32_e32 v12, v0
	v_mov_b32_e32 v13, v0
	v_mov_b32_e32 v14, v0
	v_mov_b32_e32 v15, v0
	v_mov_b32_e32 v24, v0
	v_mov_b32_e32 v25, v0
	v_mov_b32_e32 v26, v0
	v_mov_b32_e32 v27, v0
	v_mov_b32_e32 v28, v0
	v_mov_b32_e32 v29, v0
	v_mov_b32_e32 v30, v0
	v_mov_b32_e32 v31, v0
	v_mov_b32_e32 v40, v0
	v_mov_b32_e32 v41, v0
	v_mov_b32_e32 v42, v0
	v_mov_b32_e32 v43, v0
	v_mov_b32_e32 v44, v0
	v_mov_b32_e32 v45, v0
	v_mov_b32_e32 v46, v0
	v_mov_b32_e32 v47, v0
	v_mov_b32_e32 v56, v0
	v_mov_b32_e32 v57, v0
	v_mov_b32_e32 v58, v0
	v_mov_b32_e32 v59, v0
	v_mov_b32_e32 v60, v0
	v_mov_b32_e32 v61, v0
	v_mov_b32_e32 v62, v0
	v_mov_b32_e32 v63, v0
	v_mov_b32_e32 v64, v0
	v_mov_b32_e32 v65, v0
	v_mov_b32_e32 v66, v0
	v_mov_b32_e32 v67, v0
	v_mov_b32_e32 v68, v0
	v_mov_b32_e32 v69, v0
	v_mov_b32_e32 v70, v0
	v_mov_b32_e32 v71, v0
	v_mov_b32_e32 v80, v0
	v_mov_b32_e32 v81, v0
	v_mov_b32_e32 v82, v0
	v_mov_b32_e32 v83, v0
	v_mov_b32_e32 v84, v0
	v_mov_b32_e32 v85, v0
	v_mov_b32_e32 v86, v0
	v_mov_b32_e32 v87, v0
	v_mov_b32_e32 v96, v0
	v_mov_b32_e32 v97, v0
	v_mov_b32_e32 v98, v0
	v_mov_b32_e32 v99, v0
	v_mov_b32_e32 v100, v0
	v_mov_b32_e32 v101, v0
	v_mov_b32_e32 v102, v0
	v_mov_b32_e32 v103, v0
	v_mov_b32_e32 v112, v0
	v_mov_b32_e32 v113, v0
	v_mov_b32_e32 v114, v0
	v_mov_b32_e32 v115, v0
	v_mov_b32_e32 v116, v0
	v_mov_b32_e32 v117, v0
	v_mov_b32_e32 v118, v0
	v_mov_b32_e32 v119, v0
	v_mov_b32_e32 v72, v0
	v_mov_b32_e32 v73, v0
	v_mov_b32_e32 v74, v0
	v_mov_b32_e32 v75, v0
	v_mov_b32_e32 v76, v0
	v_mov_b32_e32 v77, v0
	v_mov_b32_e32 v78, v0
	v_mov_b32_e32 v79, v0
	v_mov_b32_e32 v88, v0
	v_mov_b32_e32 v89, v0
	v_mov_b32_e32 v90, v0
	v_mov_b32_e32 v91, v0
	v_mov_b32_e32 v92, v0
	v_mov_b32_e32 v93, v0
	v_mov_b32_e32 v94, v0
	v_mov_b32_e32 v95, v0
	v_mov_b32_e32 v104, v0
	v_mov_b32_e32 v105, v0
	v_mov_b32_e32 v106, v0
	v_mov_b32_e32 v107, v0
	v_mov_b32_e32 v108, v0
	v_mov_b32_e32 v109, v0
	v_mov_b32_e32 v110, v0
	v_mov_b32_e32 v111, v0
	v_mov_b32_e32 v120, v0
	v_mov_b32_e32 v121, v0
	v_mov_b32_e32 v122, v0
	v_mov_b32_e32 v123, v0
	v_mov_b32_e32 v124, v0
	v_mov_b32_e32 v125, v0
	v_mov_b32_e32 v126, v0
	v_mov_b32_e32 v127, v0
	s_cmp_eq_u32 s42, 1
	s_cselect_b32 s101, 0x7fffffff, -2
.LBB0_370:
	ds_read_b128 v[144:147], v151
	ds_read_b128 v[156:159], v151 offset:1024
	ds_read_b128 v[160:163], v151 offset:2048
	ds_read_b128 v[164:167], v151 offset:3072
	ds_read_b128 v[168:171], v152
	ds_read_b128 v[172:175], v152 offset:1024
	ds_read_b128 v[176:179], v152 offset:2048
	ds_read_b128 v[180:183], v152 offset:3072
	s_add_u32 s24, s22, 0xfff50080
	s_addc_u32 s25, s23, -1
	s_cmp_eq_u32 s48, 40
	s_cselect_b32 s27, s5, s25
	s_cselect_b32 s26, s4, s24
	s_cselect_b32 s25, s21, s47
	s_cselect_b32 s24, s20, s46
	v_lshl_add_u64 v[218:219], s[22:23], 0, v[136:137]
	s_add_i32 m0, s29, 0xc000
	ds_read_b128 v[184:187], v153
	ds_read_b128 v[188:191], v153 offset:1024
	ds_read_b128 v[192:195], v153 offset:2048
	ds_read_b128 v[198:201], v153 offset:3072
	ds_read_b128 v[202:205], v153 offset:4096
	ds_read_b128 v[206:209], v153 offset:5120
	ds_read_b128 v[210:213], v153 offset:6144
	ds_read_b128 v[214:217], v153 offset:7168
	global_load_lds_dwordx4 v[218:219], off
	v_lshl_add_u64 v[218:219], s[22:23], 0, v[138:139]
	s_add_i32 m0, s29, 0xe000
	s_nop 0
	global_load_lds_dwordx4 v[218:219], off
	s_cmp_eq_u32 s48, s101
	s_cbranch_scc1 .Lrw3_r0
	s_waitcnt vmcnt(8)
; #define PG8_STAGE(bufoff, gbase, voff) do { _Pragma("unroll") for (int _i = 0; _i < 2; ++_i) \
;         __builtin_amdgcn_global_load_lds((const unsigned*)((const char*)(gbase) + (voff)[_i]), (PG8_LAS unsigned*)(lds + (bufoff) + ldsw + _i * 8192), 16, 0, 0); } while (0)
; #define PG8_LDA(dst, b, h) do { _Pragma("unroll") for (int m = 0; m < 4; ++m) _Pragma("unroll") for (int k = 0; k < 2; ++k) dst[m][k] = *(const PG8_LAS bf16x8*)(lds + PG8_SA(b, h) + aoff + m * 2048 + k * 1024); } while (0)
; #define PG8_MMA(ai, bj, At, Bt) do { __builtin_amdgcn_s_setprio(1); _Pragma("unroll") for (int m = 0; m < 4; ++m) _Pragma("unroll") for (int n = 0; n < 2; ++n) _Pragma("unroll") for (int k = 0; k < 2; ++k) \
;         acc[ai][bj][m][n] = __builtin_amdgcn_mfma_f32_16x16x32_bf16(Bt[n][k], At[m][k], acc[ai][bj][m][n], 0, 0, 0); __builtin_amdgcn_s_setprio(0); } while (0)
; #define PG8_WAIT_V(n) asm volatile("s_waitcnt vmcnt(" #n ")" ::: "memory")
; #define PG8_WAIT_L(n) asm volatile("s_waitcnt lgkmcnt(" #n ")" ::: "memory")
; #define PG8_BAR __builtin_amdgcn_s_barrier()
; #define PG8_SCHED __builtin_amdgcn_sched_barrier(0)
; template <class Epi, class Sched, bool ALIGN_EPI = false, bool SP2 = false>
; __device__ __forceinline__ void gemm_phase(PG8_LAS unsigned char* lds, const Gemm g, const Sched& S, const Epi& E) {
;     ...
;             PG8_WAIT_V(8); PG8_WAIT_L(0); PG8_BAR; PG8_MMA(0, 0, At, B0); PG8_MMA(0, 1, At, B1); PG8_BAR; PG8_SCHED;
;             PG8_LDA(At, 0, 1); PG8_STAGE(PG8_SB(0, 0), b2, voffB); PG8_STAGE(PG8_SB(0, 1), b2 + hstep, voffB); PG8_STAGE(PG8_SA(0, 0), a2, voffA);
;             PG8_WAIT_V(8); PG8_WAIT_L(0); PG8_BAR; PG8_MMA(1, 0, At, B0); PG8_MMA(1, 1, At, B1); PG8_BAR; PG8_SCHED;
.Lrw3_b0:
	s_waitcnt lgkmcnt(0)
	s_barrier
	s_setprio 1
	s_waitcnt lgkmcnt(0)
	v_mfma_f32_16x16x32_bf16 v[124:127], v[144:147], v[184:187], v[124:127]
	v_mfma_f32_16x16x32_bf16 v[120:123], v[160:163], v[184:187], v[120:123]
	v_mfma_f32_16x16x32_bf16 v[108:111], v[144:147], v[192:195], v[108:111]
	v_mfma_f32_16x16x32_bf16 v[104:107], v[160:163], v[192:195], v[104:107]
	v_mfma_f32_16x16x32_bf16 v[92:95], v[144:147], v[202:205], v[92:95]
	v_mfma_f32_16x16x32_bf16 v[88:91], v[160:163], v[202:205], v[88:91]
	v_mfma_f32_16x16x32_bf16 v[76:79], v[144:147], v[210:213], v[76:79]
	v_mfma_f32_16x16x32_bf16 v[72:75], v[160:163], v[210:213], v[72:75]
	v_mfma_f32_16x16x32_bf16 v[124:127], v[156:159], v[188:191], v[124:127]
	v_mfma_f32_16x16x32_bf16 v[120:123], v[164:167], v[188:191], v[120:123]
	v_mfma_f32_16x16x32_bf16 v[108:111], v[156:159], v[198:201], v[108:111]
	v_mfma_f32_16x16x32_bf16 v[104:107], v[164:167], v[198:201], v[104:107]
	v_mfma_f32_16x16x32_bf16 v[92:95], v[156:159], v[206:209], v[92:95]
	v_mfma_f32_16x16x32_bf16 v[88:91], v[164:167], v[206:209], v[88:91]
	v_mfma_f32_16x16x32_bf16 v[76:79], v[156:159], v[214:217], v[76:79]
	v_mfma_f32_16x16x32_bf16 v[72:75], v[164:167], v[214:217], v[72:75]
	s_setprio 0
	s_setprio 1
	v_mfma_f32_16x16x32_bf16 v[116:119], v[168:171], v[184:187], v[116:119]
	v_mfma_f32_16x16x32_bf16 v[112:115], v[176:179], v[184:187], v[112:115]
	v_mfma_f32_16x16x32_bf16 v[100:103], v[168:171], v[192:195], v[100:103]
	v_mfma_f32_16x16x32_bf16 v[96:99], v[176:179], v[192:195], v[96:99]
	v_mfma_f32_16x16x32_bf16 v[84:87], v[168:171], v[202:205], v[84:87]
	v_mfma_f32_16x16x32_bf16 v[80:83], v[176:179], v[202:205], v[80:83]
	v_mfma_f32_16x16x32_bf16 v[68:71], v[168:171], v[210:213], v[68:71]
	v_mfma_f32_16x16x32_bf16 v[64:67], v[176:179], v[210:213], v[64:67]
	v_mfma_f32_16x16x32_bf16 v[116:119], v[172:175], v[188:191], v[116:119]
	v_mfma_f32_16x16x32_bf16 v[112:115], v[180:183], v[188:191], v[112:115]
	v_mfma_f32_16x16x32_bf16 v[100:103], v[172:175], v[198:201], v[100:103]
	v_mfma_f32_16x16x32_bf16 v[96:99], v[180:183], v[198:201], v[96:99]
	v_mfma_f32_16x16x32_bf16 v[84:87], v[172:175], v[206:209], v[84:87]
	v_mfma_f32_16x16x32_bf16 v[80:83], v[180:183], v[206:209], v[80:83]
	v_mfma_f32_16x16x32_bf16 v[68:71], v[172:175], v[214:217], v[68:71]
	v_mfma_f32_16x16x32_bf16 v[64:67], v[180:183], v[214:217], v[64:67]
	s_setprio 0
	s_barrier
	s_add_i32 s49, s40, s28
	v_lshl_add_u64 v[218:219], s[24:25], 0, v[130:131]
	s_mov_b32 m0, s49
	ds_read_b128 v[184:187], v153 offset:16384
	ds_read_b128 v[188:191], v153 offset:17408
	ds_read_b128 v[192:195], v153 offset:18432
	ds_read_b128 v[198:201], v153 offset:19456
	ds_read_b128 v[202:205], v153 offset:20480
	ds_read_b128 v[206:209], v153 offset:21504
	ds_read_b128 v[210:213], v153 offset:22528
	ds_read_b128 v[214:217], v153 offset:23552
	global_load_lds_dwordx4 v[218:219], off
	s_add_i32 m0, s49, 0x2000
	s_add_u32 s50, s24, 0xb0000
	v_lshl_add_u64 v[220:221], s[24:25], 0, v[134:135]
	s_addc_u32 s51, s25, 0
	s_add_i32 s49, s41, s28
	global_load_lds_dwordx4 v[220:221], off
	v_lshl_add_u64 v[222:223], s[50:51], 0, v[130:131]
	s_mov_b32 m0, s49
	v_lshl_add_u64 v[224:225], s[26:27], 0, v[132:133]
	global_load_lds_dwordx4 v[222:223], off
	v_lshl_add_u64 v[222:223], s[50:51], 0, v[134:135]
	s_add_i32 m0, s49, 0x2000
	s_nop 0
	global_load_lds_dwordx4 v[222:223], off
	v_lshl_add_u64 v[222:223], s[26:27], 0, v[128:129]
	s_mov_b32 m0, s29
	s_nop 0
	global_load_lds_dwordx4 v[222:223], off
	s_mov_b32 m0, s30
	s_nop 0
	global_load_lds_dwordx4 v[224:225], off
	s_cmp_eq_u32 s48, s101
	s_cbranch_scc1 .Lrw3_r1
	s_waitcnt vmcnt(8)
.Lrw3_b1:
	s_waitcnt lgkmcnt(0)
	s_barrier
	s_setprio 1
	s_waitcnt lgkmcnt(0)
	v_mfma_f32_16x16x32_bf16 v[60:63], v[144:147], v[184:187], v[60:63]
	v_mfma_f32_16x16x32_bf16 v[56:59], v[160:163], v[184:187], v[56:59]
	v_mfma_f32_16x16x32_bf16 v[44:47], v[144:147], v[192:195], v[44:47]
	v_mfma_f32_16x16x32_bf16 v[40:43], v[160:163], v[192:195], v[40:43]
	v_mfma_f32_16x16x32_bf16 v[28:31], v[144:147], v[202:205], v[28:31]
	v_mfma_f32_16x16x32_bf16 v[24:27], v[160:163], v[202:205], v[24:27]
	v_mfma_f32_16x16x32_bf16 v[12:15], v[144:147], v[210:213], v[12:15]
	v_mfma_f32_16x16x32_bf16 v[8:11], v[160:163], v[210:213], v[8:11]
	v_mfma_f32_16x16x32_bf16 v[60:63], v[156:159], v[188:191], v[60:63]
	v_mfma_f32_16x16x32_bf16 v[56:59], v[164:167], v[188:191], v[56:59]
	v_mfma_f32_16x16x32_bf16 v[44:47], v[156:159], v[198:201], v[44:47]
	v_mfma_f32_16x16x32_bf16 v[40:43], v[164:167], v[198:201], v[40:43]
	v_mfma_f32_16x16x32_bf16 v[28:31], v[156:159], v[206:209], v[28:31]
	v_mfma_f32_16x16x32_bf16 v[24:27], v[164:167], v[206:209], v[24:27]
	v_mfma_f32_16x16x32_bf16 v[12:15], v[156:159], v[214:217], v[12:15]
	v_mfma_f32_16x16x32_bf16 v[8:11], v[164:167], v[214:217], v[8:11]
	s_setprio 0
	s_setprio 1
	v_mfma_f32_16x16x32_bf16 v[52:55], v[168:171], v[184:187], v[52:55]
	v_mfma_f32_16x16x32_bf16 v[48:51], v[176:179], v[184:187], v[48:51]
	v_mfma_f32_16x16x32_bf16 v[36:39], v[168:171], v[192:195], v[36:39]
	v_mfma_f32_16x16x32_bf16 v[32:35], v[176:179], v[192:195], v[32:35]
	v_mfma_f32_16x16x32_bf16 v[20:23], v[168:171], v[202:205], v[20:23]
	v_mfma_f32_16x16x32_bf16 v[16:19], v[176:179], v[202:205], v[16:19]
	v_mfma_f32_16x16x32_bf16 v[4:7], v[168:171], v[210:213], v[4:7]
	v_mfma_f32_16x16x32_bf16 v[0:3], v[176:179], v[210:213], v[0:3]
	v_mfma_f32_16x16x32_bf16 v[52:55], v[172:175], v[188:191], v[52:55]
	v_mfma_f32_16x16x32_bf16 v[48:51], v[180:183], v[188:191], v[48:51]
	v_mfma_f32_16x16x32_bf16 v[36:39], v[172:175], v[198:201], v[36:39]
	v_mfma_f32_16x16x32_bf16 v[32:35], v[180:183], v[198:201], v[32:35]
	v_mfma_f32_16x16x32_bf16 v[20:23], v[172:175], v[206:209], v[20:23]
	v_mfma_f32_16x16x32_bf16 v[16:19], v[180:183], v[206:209], v[16:19]
	v_mfma_f32_16x16x32_bf16 v[4:7], v[172:175], v[214:217], v[4:7]
	v_mfma_f32_16x16x32_bf16 v[0:3], v[180:183], v[214:217], v[0:3]
	s_setprio 0
	s_barrier
; #define PG8_STAGE(bufoff, gbase, voff) do { _Pragma("unroll") for (int _i = 0; _i < 2; ++_i) \
;         __builtin_amdgcn_global_load_lds((const unsigned*)((const char*)(gbase) + (voff)[_i]), (PG8_LAS unsigned*)(lds + (bufoff) + ldsw + _i * 8192), 16, 0, 0); } while (0)
; #define PG8_LDA(dst, b, h) do { _Pragma("unroll") for (int m = 0; m < 4; ++m) _Pragma("unroll") for (int k = 0; k < 2; ++k) dst[m][k] = *(const PG8_LAS bf16x8*)(lds + PG8_SA(b, h) + aoff + m * 2048 + k * 1024); } while (0)
; #define PG8_LDB(dst, b, h) do { _Pragma("unroll") for (int n = 0; n < 2; ++n) _Pragma("unroll") for (int k = 0; k < 2; ++k) dst[n][k] = *(const PG8_LAS bf16x8*)(lds + PG8_SB(b, h) + boff + n * 2048 + k * 1024); } while (0)
; #define PG8_MMA(ai, bj, At, Bt) do { __builtin_amdgcn_s_setprio(1); _Pragma("unroll") for (int m = 0; m < 4; ++m) _Pragma("unroll") for (int n = 0; n < 2; ++n) _Pragma("unroll") for (int k = 0; k < 2; ++k) \
;         acc[ai][bj][m][n] = __builtin_amdgcn_mfma_f32_16x16x32_bf16(Bt[n][k], At[m][k], acc[ai][bj][m][n], 0, 0, 0); __builtin_amdgcn_s_setprio(0); } while (0)
; #define PG8_WAIT_V(n) asm volatile("s_waitcnt vmcnt(" #n ")" ::: "memory")
; #define PG8_WAIT_L(n) asm volatile("s_waitcnt lgkmcnt(" #n ")" ::: "memory")
; #define PG8_BAR __builtin_amdgcn_s_barrier()
; #define PG8_SCHED __builtin_amdgcn_sched_barrier(0)
; template <class Epi, class Sched, bool ALIGN_EPI = false, bool SP2 = false>
; __device__ __forceinline__ void gemm_phase(PG8_LAS unsigned char* lds, const Gemm g, const Sched& S, const Epi& E) {
;     ...
;             PG8_LDB(B0, 1, 0); PG8_LDB(B1, 1, 1); PG8_SCHED; PG8_LDA(At, 1, 0); PG8_STAGE(PG8_SA(0, 1), a2 + hstep, voffA);
;             PG8_WAIT_V(8); PG8_WAIT_L(0); PG8_BAR; PG8_MMA(0, 0, At, B0); PG8_MMA(0, 1, At, B1); PG8_BAR; PG8_SCHED;
	s_add_i32 s49, 0, 0x18000
	v_add_u32_e32 v155, s49, v149
	s_add_i32 s50, 0, 0x1c000
	ds_read_b128 v[144:147], v155
	ds_read_b128 v[156:159], v155 offset:1024
	ds_read_b128 v[160:163], v155 offset:2048
	ds_read_b128 v[164:167], v155 offset:3072
	v_add_u32_e32 v155, s50, v149
	ds_read_b128 v[168:171], v155
	ds_read_b128 v[172:175], v155 offset:1024
	ds_read_b128 v[176:179], v155 offset:2048
	ds_read_b128 v[180:183], v155 offset:3072
	s_add_u32 s26, s26, 0xb0000
	s_addc_u32 s27, s27, 0
	s_mov_b32 m0, s31
	v_lshl_add_u64 v[226:227], s[26:27], 0, v[128:129]
	ds_read_b128 v[184:187], v153 offset:32768
	ds_read_b128 v[188:191], v153 offset:33792
	ds_read_b128 v[192:195], v153 offset:34816
	ds_read_b128 v[198:201], v153 offset:35840
	ds_read_b128 v[202:205], v153 offset:36864
	ds_read_b128 v[206:209], v153 offset:37888
	ds_read_b128 v[210:213], v153 offset:38912
	ds_read_b128 v[214:217], v153 offset:39936
	global_load_lds_dwordx4 v[226:227], off
	v_lshl_add_u64 v[226:227], s[26:27], 0, v[132:133]
	s_mov_b32 m0, s33
	s_nop 0
	global_load_lds_dwordx4 v[226:227], off
	s_waitcnt vmcnt(8)
	s_waitcnt lgkmcnt(0)
	s_barrier
	s_setprio 1
	s_waitcnt lgkmcnt(0)
	v_mfma_f32_16x16x32_bf16 v[124:127], v[144:147], v[184:187], v[124:127]
	v_mfma_f32_16x16x32_bf16 v[120:123], v[160:163], v[184:187], v[120:123]
	v_mfma_f32_16x16x32_bf16 v[108:111], v[144:147], v[192:195], v[108:111]
	v_mfma_f32_16x16x32_bf16 v[104:107], v[160:163], v[192:195], v[104:107]
	v_mfma_f32_16x16x32_bf16 v[92:95], v[144:147], v[202:205], v[92:95]
	v_mfma_f32_16x16x32_bf16 v[88:91], v[160:163], v[202:205], v[88:91]
	v_mfma_f32_16x16x32_bf16 v[76:79], v[144:147], v[210:213], v[76:79]
	v_mfma_f32_16x16x32_bf16 v[72:75], v[160:163], v[210:213], v[72:75]
	v_mfma_f32_16x16x32_bf16 v[124:127], v[156:159], v[188:191], v[124:127]
	v_mfma_f32_16x16x32_bf16 v[120:123], v[164:167], v[188:191], v[120:123]
	v_mfma_f32_16x16x32_bf16 v[108:111], v[156:159], v[198:201], v[108:111]
	v_mfma_f32_16x16x32_bf16 v[104:107], v[164:167], v[198:201], v[104:107]
	v_mfma_f32_16x16x32_bf16 v[92:95], v[156:159], v[206:209], v[92:95]
	v_mfma_f32_16x16x32_bf16 v[88:91], v[164:167], v[206:209], v[88:91]
	v_mfma_f32_16x16x32_bf16 v[76:79], v[156:159], v[214:217], v[76:79]
	v_mfma_f32_16x16x32_bf16 v[72:75], v[164:167], v[214:217], v[72:75]
	s_setprio 0
	s_setprio 1
	v_mfma_f32_16x16x32_bf16 v[116:119], v[168:171], v[184:187], v[116:119]
	v_mfma_f32_16x16x32_bf16 v[112:115], v[176:179], v[184:187], v[112:115]
	v_mfma_f32_16x16x32_bf16 v[100:103], v[168:171], v[192:195], v[100:103]
	v_mfma_f32_16x16x32_bf16 v[96:99], v[176:179], v[192:195], v[96:99]
	v_mfma_f32_16x16x32_bf16 v[84:87], v[168:171], v[202:205], v[84:87]
	v_mfma_f32_16x16x32_bf16 v[80:83], v[176:179], v[202:205], v[80:83]
	v_mfma_f32_16x16x32_bf16 v[68:71], v[168:171], v[210:213], v[68:71]
	v_mfma_f32_16x16x32_bf16 v[64:67], v[176:179], v[210:213], v[64:67]
	v_mfma_f32_16x16x32_bf16 v[116:119], v[172:175], v[188:191], v[116:119]
	v_mfma_f32_16x16x32_bf16 v[112:115], v[180:183], v[188:191], v[112:115]
	v_mfma_f32_16x16x32_bf16 v[100:103], v[172:175], v[198:201], v[100:103]
	v_mfma_f32_16x16x32_bf16 v[96:99], v[180:183], v[198:201], v[96:99]
	v_mfma_f32_16x16x32_bf16 v[84:87], v[172:175], v[206:209], v[84:87]
	v_mfma_f32_16x16x32_bf16 v[80:83], v[180:183], v[206:209], v[80:83]
	v_mfma_f32_16x16x32_bf16 v[68:71], v[172:175], v[214:217], v[68:71]
	v_mfma_f32_16x16x32_bf16 v[64:67], v[180:183], v[214:217], v[64:67]
	s_setprio 0
	s_barrier
; #define PG8_STAGE(bufoff, gbase, voff) do { _Pragma("unroll") for (int _i = 0; _i < 2; ++_i) \
;         __builtin_amdgcn_global_load_lds((const unsigned*)((const char*)(gbase) + (voff)[_i]), (PG8_LAS unsigned*)(lds + (bufoff) + ldsw + _i * 8192), 16, 0, 0); } while (0)
; #define PG8_LDA(dst, b, h) do { _Pragma("unroll") for (int m = 0; m < 4; ++m) _Pragma("unroll") for (int k = 0; k < 2; ++k) dst[m][k] = *(const PG8_LAS bf16x8*)(lds + PG8_SA(b, h) + aoff + m * 2048 + k * 1024); } while (0)
; #define PG8_MMA(ai, bj, At, Bt) do { __builtin_amdgcn_s_setprio(1); _Pragma("unroll") for (int m = 0; m < 4; ++m) _Pragma("unroll") for (int n = 0; n < 2; ++n) _Pragma("unroll") for (int k = 0; k < 2; ++k) \
;         acc[ai][bj][m][n] = __builtin_amdgcn_mfma_f32_16x16x32_bf16(Bt[n][k], At[m][k], acc[ai][bj][m][n], 0, 0, 0); __builtin_amdgcn_s_setprio(0); } while (0)
; #define PG8_WAIT_V(n) asm volatile("s_waitcnt vmcnt(" #n ")" ::: "memory")
; #define PG8_WAIT_L(n) asm volatile("s_waitcnt lgkmcnt(" #n ")" ::: "memory")
; #define PG8_BAR __builtin_amdgcn_s_barrier()
; #define PG8_SCHED __builtin_amdgcn_sched_barrier(0)
; template <class Epi, class Sched, bool ALIGN_EPI = false, bool SP2 = false>
; __device__ __forceinline__ void gemm_phase(PG8_LAS unsigned char* lds, const Gemm g, const Sched& S, const Epi& E) {
;     ...
;             PG8_LDA(At, 1, 1); PG8_STAGE(PG8_SB(1, 0), b3, voffB); PG8_STAGE(PG8_SB(1, 1), b3 + hstep, voffB); PG8_STAGE(PG8_SA(1, 0), a3, voffA);
;             PG8_WAIT_V(8); PG8_WAIT_L(0); PG8_BAR; PG8_MMA(1, 0, At, B0); PG8_MMA(1, 1, At, B1); PG8_BAR; PG8_SCHED;
	s_add_i32 s26, s49, s28
	v_lshl_add_u64 v[218:219], v[218:219], 0, s[16:17]
	s_mov_b32 m0, s26
	ds_read_b128 v[184:187], v153 offset:49152
	ds_read_b128 v[188:191], v153 offset:50176
	ds_read_b128 v[192:195], v153 offset:51200
	ds_read_b128 v[198:201], v153 offset:52224
	ds_read_b128 v[202:205], v153 offset:53248
	ds_read_b128 v[206:209], v153 offset:54272
	ds_read_b128 v[210:213], v153 offset:55296
	ds_read_b128 v[214:217], v153 offset:56320
	global_load_lds_dwordx4 v[218:219], off
	s_add_i32 m0, s26, 0x2000
	s_add_u32 s24, s24, 0xb0080
	v_lshl_add_u64 v[218:219], v[220:221], 0, s[16:17]
	s_addc_u32 s25, s25, 0
	s_add_i32 s26, s50, s28
	global_load_lds_dwordx4 v[218:219], off
	v_lshl_add_u64 v[218:219], s[24:25], 0, v[130:131]
	s_mov_b32 m0, s26
	s_nop 0
	global_load_lds_dwordx4 v[218:219], off
	v_lshl_add_u64 v[218:219], s[24:25], 0, v[134:135]
	s_add_i32 m0, s26, 0x2000
	s_nop 0
	global_load_lds_dwordx4 v[218:219], off
	v_lshl_add_u64 v[218:219], v[222:223], 0, s[16:17]
	s_mov_b32 m0, s37
	s_nop 0
	global_load_lds_dwordx4 v[218:219], off
	v_lshl_add_u64 v[218:219], v[224:225], 0, s[16:17]
	s_mov_b32 m0, s38
	s_nop 0
	global_load_lds_dwordx4 v[218:219], off
	s_waitcnt vmcnt(8)
	s_waitcnt lgkmcnt(0)
	s_barrier
	s_setprio 1
	s_waitcnt lgkmcnt(0)
	v_mfma_f32_16x16x32_bf16 v[60:63], v[144:147], v[184:187], v[60:63]
	v_mfma_f32_16x16x32_bf16 v[56:59], v[160:163], v[184:187], v[56:59]
	v_mfma_f32_16x16x32_bf16 v[44:47], v[144:147], v[192:195], v[44:47]
	v_mfma_f32_16x16x32_bf16 v[40:43], v[160:163], v[192:195], v[40:43]
	v_mfma_f32_16x16x32_bf16 v[28:31], v[144:147], v[202:205], v[28:31]
	v_mfma_f32_16x16x32_bf16 v[24:27], v[160:163], v[202:205], v[24:27]
	v_mfma_f32_16x16x32_bf16 v[12:15], v[144:147], v[210:213], v[12:15]
	v_mfma_f32_16x16x32_bf16 v[8:11], v[160:163], v[210:213], v[8:11]
	v_mfma_f32_16x16x32_bf16 v[60:63], v[156:159], v[188:191], v[60:63]
	v_mfma_f32_16x16x32_bf16 v[56:59], v[164:167], v[188:191], v[56:59]
	v_mfma_f32_16x16x32_bf16 v[44:47], v[156:159], v[198:201], v[44:47]
	v_mfma_f32_16x16x32_bf16 v[40:43], v[164:167], v[198:201], v[40:43]
	v_mfma_f32_16x16x32_bf16 v[28:31], v[156:159], v[206:209], v[28:31]
	v_mfma_f32_16x16x32_bf16 v[24:27], v[164:167], v[206:209], v[24:27]
	v_mfma_f32_16x16x32_bf16 v[12:15], v[156:159], v[214:217], v[12:15]
	v_mfma_f32_16x16x32_bf16 v[8:11], v[164:167], v[214:217], v[8:11]
	s_setprio 0
	s_setprio 1
	v_mfma_f32_16x16x32_bf16 v[52:55], v[168:171], v[184:187], v[52:55]
	v_mfma_f32_16x16x32_bf16 v[48:51], v[176:179], v[184:187], v[48:51]
	v_mfma_f32_16x16x32_bf16 v[36:39], v[168:171], v[192:195], v[36:39]
	v_mfma_f32_16x16x32_bf16 v[32:35], v[176:179], v[192:195], v[32:35]
	v_mfma_f32_16x16x32_bf16 v[20:23], v[168:171], v[202:205], v[20:23]
	v_mfma_f32_16x16x32_bf16 v[16:19], v[176:179], v[202:205], v[16:19]
	v_mfma_f32_16x16x32_bf16 v[4:7], v[168:171], v[210:213], v[4:7]
	v_mfma_f32_16x16x32_bf16 v[0:3], v[176:179], v[210:213], v[0:3]
	v_mfma_f32_16x16x32_bf16 v[52:55], v[172:175], v[188:191], v[52:55]
	v_mfma_f32_16x16x32_bf16 v[48:51], v[180:183], v[188:191], v[48:51]
	v_mfma_f32_16x16x32_bf16 v[36:39], v[172:175], v[198:201], v[36:39]
	v_mfma_f32_16x16x32_bf16 v[32:35], v[180:183], v[198:201], v[32:35]
	v_mfma_f32_16x16x32_bf16 v[20:23], v[172:175], v[206:209], v[20:23]
	v_mfma_f32_16x16x32_bf16 v[16:19], v[180:183], v[206:209], v[16:19]
	v_mfma_f32_16x16x32_bf16 v[4:7], v[172:175], v[214:217], v[4:7]
	v_mfma_f32_16x16x32_bf16 v[0:3], v[180:183], v[214:217], v[0:3]
	s_setprio 0
	s_barrier
	s_add_i32 s48, s48, 2
	s_add_u32 s22, s22, 0x100
	s_addc_u32 s23, s23, 0
	s_add_u32 s46, s46, 0x100
	s_addc_u32 s47, s47, 0
	s_cmp_gt_u32 s48, 41
	s_cbranch_scc0 .LBB0_370
	s_branch .Lrw3_x

; __device__ __forceinline__ unsigned cvt_pk_bf16(float lo, float hi) { unsigned r; asm volatile("v_cvt_pk_bf16_f32 %0, %1, %2" : "=v"(r) : "v"(lo), "v"(hi)); return r; }
; #define PG8_BAR __builtin_amdgcn_s_barrier()
;     __device__ __forceinline__ void operator()(const f32x4 (&acc)[2][2][4][2], const Unit& u, int wr, int wc, int fr, int fq) const {
;         const int row0 = u.pm * BM + wr * 64 + fr, col0 = u.pn * BM + wc * 32 + 8 * fq;
; #pragma unroll
;         for (int ai = 0; ai < 2; ++ai)
; #pragma unroll
;             for (int m = 0; m < 4; ++m) {
;                 const int row = row0 + ai * HALF + m * 16; float s = 0.f;
; #pragma unroll
;                 for (int bj = 0; bj < 2; ++bj) {
;                     const f32x4 v0 = acc[ai][bj][m][0], v1 = acc[ai][bj][m][1];
;                     s += (v0[0] * v0[0] + v0[1] * v0[1]) + (v0[2] * v0[2] + v0[3] * v0[3]) + (v1[0] * v1[0] + v1[1] * v1[1]) + (v1[2] * v1[2] + v1[3] * v1[3]);
;                     u32x4 w; w.x = cvt_pk_bf16(v0[0], v0[1]); w.y = cvt_pk_bf16(v0[2], v0[3]); w.z = cvt_pk_bf16(v1[0], v1[1]); w.w = cvt_pk_bf16(v1[2], v1[3]);
;                     *(u32x4*)(O + (size_t)row * 1024 + col0 + bj * HALF) = w;
;                 }
;                 s += __shfl_xor(s, 16); s += __shfl_xor(s, 32);
;                 if (fq == 0) rsq[(size_t)row * 16 + u.pn * 4 + wc] = s;
;             }
;     }
; template <class Epi, class Sched, bool ALIGN_EPI = false, bool SP2 = false>
; __device__ __forceinline__ void gemm_phase(PG8_LAS unsigned char* lds, const Gemm g, const Sched& S, const Epi& E) {
;     ...
;         if constexpr (ALIGN_EPI) { if (wr == 0) PG8_BAR; }
;         if constexpr (!Epi::AFTER_DRAIN) { E(acc, cur, wr, wc, fr, fq); S.done(cur); }
.Lrw3_r1:
	s_waitcnt vmcnt(24)
	s_branch .Lrw3_b1
.Lrw3_x:
	s_and_b64 vcc, exec, s[18:19]
	s_cbranch_vccz .LBB0_373
	s_barrier
.LBB0_373:
	v_mul_f32_e32 v155, v125, v125
	v_mul_f32_e32 v158, v127, v127
	v_fmac_f32_e32 v155, v124, v124
	v_fmac_f32_e32 v158, v126, v126
	v_add_f32_e32 v155, v155, v158
	v_mul_f32_e32 v158, v121, v121
	v_fmac_f32_e32 v158, v120, v120
	v_cvt_pk_bf16_f32 v124, v124, v125
	v_cvt_pk_bf16_f32 v125, v126, v127
	v_cvt_pk_bf16_f32 v126, v120, v121
	v_mul_f32_e32 v120, v117, v117
	v_mul_f32_e32 v121, v119, v119
	v_fmac_f32_e32 v120, v116, v116
	v_fmac_f32_e32 v121, v118, v118
	v_add_f32_e32 v120, v120, v121
	v_mul_f32_e32 v121, v113, v113
	v_fmac_f32_e32 v121, v112, v112
	v_add_f32_e32 v155, v155, v158
	v_mul_f32_e32 v158, v123, v123
	v_add_f32_e32 v120, v120, v121
	v_mul_f32_e32 v121, v115, v115
	v_fmac_f32_e32 v158, v122, v122
	v_fmac_f32_e32 v121, v114, v114
	v_add_f32_e32 v155, v158, v155
	v_cvt_pk_bf16_f32 v127, v122, v123
	v_add_f32_e32 v120, v121, v120
	v_and_b32_e32 v122, 64, v154
	v_add_f32_e32 v121, v155, v120
	v_xor_b32_e32 v120, 16, v154
	v_add_u32_e32 v155, 64, v122
	v_lshl_add_u32 v146, s45, 8, v148
	v_cmp_lt_i32_e32 vcc, v120, v155
	v_ashrrev_i32_e32 v147, 31, v146
	v_lshl_or_b32 v144, s12, 8, v150
	v_cndmask_b32_e32 v120, v154, v120, vcc
	v_lshlrev_b64 v[156:157], 11, v[146:147]
	v_lshlrev_b32_e32 v120, 2, v120
	v_ashrrev_i32_e32 v145, 31, v144
	ds_bpermute_b32 v158, v120, v121
	v_lshl_add_u64 v[122:123], s[84:85], 0, v[156:157]
	v_lshl_add_u64 v[156:157], v[144:145], 1, v[122:123]
	global_store_dwordx4 v[156:157], v[124:127], off
	v_cvt_pk_bf16_f32 v122, v116, v117
	v_xor_b32_e32 v116, 32, v154
	v_cmp_lt_i32_e32 vcc, v116, v155
	s_waitcnt lgkmcnt(0)
	v_add_f32_e32 v117, v121, v158
	s_lshl_b32 s22, s12, 2
	v_cndmask_b32_e32 v116, v154, v116, vcc
	v_lshlrev_b32_e32 v116, 2, v116
	ds_bpermute_b32 v121, v116, v117
	s_ashr_i32 s23, s22, 31
	v_cvt_pk_bf16_f32 v123, v118, v119
	v_cvt_pk_bf16_f32 v124, v112, v113
	v_cvt_pk_bf16_f32 v125, v114, v115
	global_store_dwordx4 v[156:157], v[122:125], off offset:256
	s_and_saveexec_b64 s[24:25], s[0:1]
	s_cbranch_execz .LBB0_375
	v_readlane_b32 s26, v253, 49
	v_lshlrev_b64 v[112:113], 6, v[146:147]
	v_readlane_b32 s27, v253, 50
	s_lshl_b32 s12, s36, 2
	s_waitcnt lgkmcnt(0)
	v_add_f32_e32 v114, v117, v121
	v_lshl_add_u64 v[112:113], s[26:27], 0, v[112:113]
	v_lshl_add_u64 v[112:113], s[22:23], 2, v[112:113]
	v_lshl_add_u64 v[112:113], v[112:113], 0, s[12:13]
	global_store_dword v[112:113], v114, off

; #define PG8_STAGE(bufoff, gbase, voff) do { _Pragma("unroll") for (int _i = 0; _i < 2; ++_i) \
;         __builtin_amdgcn_global_load_lds((const unsigned*)((const char*)(gbase) + (voff)[_i]), (PG8_LAS unsigned*)(lds + (bufoff) + ldsw + _i * 8192), 16, 0, 0); } while (0)
; #define PG8_LDA(dst, b, h) do { _Pragma("unroll") for (int m = 0; m < 4; ++m) _Pragma("unroll") for (int k = 0; k < 2; ++k) dst[m][k] = *(const PG8_LAS bf16x8*)(lds + PG8_SA(b, h) + aoff + m * 2048 + k * 1024); } while (0)
; #define PG8_LDB(dst, b, h) do { _Pragma("unroll") for (int n = 0; n < 2; ++n) _Pragma("unroll") for (int k = 0; k < 2; ++k) dst[n][k] = *(const PG8_LAS bf16x8*)(lds + PG8_SB(b, h) + boff + n * 2048 + k * 1024); } while (0)
; #define PG8_MMA(ai, bj, At, Bt) do { __builtin_amdgcn_s_setprio(1); _Pragma("unroll") for (int m = 0; m < 4; ++m) _Pragma("unroll") for (int n = 0; n < 2; ++n) _Pragma("unroll") for (int k = 0; k < 2; ++k) \
;         acc[ai][bj][m][n] = __builtin_amdgcn_mfma_f32_16x16x32_bf16(Bt[n][k], At[m][k], acc[ai][bj][m][n], 0, 0, 0); __builtin_amdgcn_s_setprio(0); } while (0)
; #define PG8_WAIT_V(n) asm volatile("s_waitcnt vmcnt(" #n ")" ::: "memory")
; #define PG8_BAR __builtin_amdgcn_s_barrier()
; template <class Epi, class Sched, bool ALIGN_EPI = false, bool SP2 = false>
; __device__ __forceinline__ void gemm_phase(PG8_LAS unsigned char* lds, const Gemm g, const Sched& S, const Epi& E) {
;     ...
;         for (int t = 0; t < nt; t += 2) {
;             const bool last = (t == nt - 2);
;             const char* a1 = cA + (size_t)(t + 1) * kstep;
;             const char* a2 = last ? nA : cA + (size_t)(t + 2) * kstep; const char* b2 = last ? nB : cB + (size_t)(t + 2) * kstep;
;             const char* a3 = a2 + kstep; const char* b3 = b2 + kstep;
;             if (last && has_next) S.a_ready(nxt);
;             if constexpr (SP2) {
;             PG8_LDB(B0, 0, 0); PG8_LDB(B1, 0, 1); PG8_SCHED; PG8_LDA(At, 0, 0); PG8_STAGE(PG8_SA(1, 1), a1 + hstep, voffA);
;             PG8_WAIT_V(8); PG8_WAIT_L(0); PG8_BAR; PG8_MMA(0, 0, At, B0); PG8_MMA(0, 1, At, B1); PG8_BAR; PG8_SCHED;
;     ...
; #pragma unroll
;         for (int a = 0; a < 2; ++a)
; #pragma unroll
;             for (int b = 0; b < 2; ++b)
; #pragma unroll
;                 for (int m = 0; m < 4; ++m)
; #pragma unroll
;                     for (int n = 0; n < 2; ++n) acc[a][b][m][n] = (f32x4){0.f, 0.f, 0.f, 0.f};
.LBB0_1238:
	s_add_u32 s18, s18, 0xb0080
	s_addc_u32 s19, s19, 0
	s_add_u32 s42, s20, 0x100
	v_mov_b32_e32 v0, 0
	s_addc_u32 s43, s21, 0
	s_mov_b32 s44, -2
	v_mov_b32_e32 v1, v0
	v_mov_b32_e32 v2, v0
	v_mov_b32_e32 v3, v0
	v_mov_b32_e32 v4, v0
	s_waitcnt lgkmcnt(0)
	v_mov_b32_e32 v5, v0
	v_mov_b32_e32 v6, v0
	v_mov_b32_e32 v7, v0
	v_mov_b32_e32 v16, v0
	v_mov_b32_e32 v17, v0
	v_mov_b32_e32 v18, v0
	v_mov_b32_e32 v19, v0
	v_mov_b32_e32 v20, v0
	v_mov_b32_e32 v21, v0
	v_mov_b32_e32 v22, v0
	v_mov_b32_e32 v23, v0
	v_mov_b32_e32 v32, v0
	v_mov_b32_e32 v33, v0
	v_mov_b32_e32 v34, v0
	v_mov_b32_e32 v35, v0
	v_mov_b32_e32 v36, v0
	v_mov_b32_e32 v37, v0
	v_mov_b32_e32 v38, v0
	v_mov_b32_e32 v39, v0
	v_mov_b32_e32 v48, v0
	v_mov_b32_e32 v49, v0
	v_mov_b32_e32 v50, v0
	v_mov_b32_e32 v51, v0
	v_mov_b32_e32 v52, v0
	v_mov_b32_e32 v53, v0
	v_mov_b32_e32 v54, v0
	v_mov_b32_e32 v55, v0
	v_mov_b32_e32 v8, v0
	v_mov_b32_e32 v9, v0
	v_mov_b32_e32 v10, v0
	v_mov_b32_e32 v11, v0
	v_mov_b32_e32 v12, v0
	v_mov_b32_e32 v13, v0
	v_mov_b32_e32 v14, v0
	v_mov_b32_e32 v15, v0
	v_mov_b32_e32 v24, v0
	v_mov_b32_e32 v25, v0
	v_mov_b32_e32 v26, v0
	v_mov_b32_e32 v27, v0
	v_mov_b32_e32 v28, v0
	v_mov_b32_e32 v29, v0
	v_mov_b32_e32 v30, v0
	v_mov_b32_e32 v31, v0
	v_mov_b32_e32 v40, v0
	v_mov_b32_e32 v41, v0
	v_mov_b32_e32 v42, v0
	v_mov_b32_e32 v43, v0
	v_mov_b32_e32 v44, v0
	v_mov_b32_e32 v45, v0
	v_mov_b32_e32 v46, v0
	v_mov_b32_e32 v47, v0
	v_mov_b32_e32 v56, v0
	v_mov_b32_e32 v57, v0
	v_mov_b32_e32 v58, v0
	v_mov_b32_e32 v59, v0
	v_mov_b32_e32 v60, v0
	v_mov_b32_e32 v61, v0
	v_mov_b32_e32 v62, v0
	v_mov_b32_e32 v63, v0
	v_mov_b32_e32 v64, v0
	v_mov_b32_e32 v65, v0
	v_mov_b32_e32 v66, v0
	v_mov_b32_e32 v67, v0
	v_mov_b32_e32 v68, v0
	v_mov_b32_e32 v69, v0
	v_mov_b32_e32 v70, v0
	v_mov_b32_e32 v71, v0
	v_mov_b32_e32 v80, v0
	v_mov_b32_e32 v81, v0
	v_mov_b32_e32 v82, v0
	v_mov_b32_e32 v83, v0
	v_mov_b32_e32 v84, v0
	v_mov_b32_e32 v85, v0
	v_mov_b32_e32 v86, v0
	v_mov_b32_e32 v87, v0
	v_mov_b32_e32 v96, v0
	v_mov_b32_e32 v97, v0
	v_mov_b32_e32 v98, v0
	v_mov_b32_e32 v99, v0
	v_mov_b32_e32 v100, v0
	v_mov_b32_e32 v101, v0
	v_mov_b32_e32 v102, v0
	v_mov_b32_e32 v103, v0
	v_mov_b32_e32 v112, v0
	v_mov_b32_e32 v113, v0
	v_mov_b32_e32 v114, v0
	v_mov_b32_e32 v115, v0
	v_mov_b32_e32 v116, v0
	v_mov_b32_e32 v117, v0
	v_mov_b32_e32 v118, v0
	v_mov_b32_e32 v119, v0
	v_mov_b32_e32 v72, v0
	v_mov_b32_e32 v73, v0
	v_mov_b32_e32 v74, v0
	v_mov_b32_e32 v75, v0
	v_mov_b32_e32 v76, v0
	v_mov_b32_e32 v77, v0
	v_mov_b32_e32 v78, v0
	v_mov_b32_e32 v79, v0
	v_mov_b32_e32 v88, v0
	v_mov_b32_e32 v89, v0
	v_mov_b32_e32 v90, v0
	v_mov_b32_e32 v91, v0
	v_mov_b32_e32 v92, v0
	v_mov_b32_e32 v93, v0
	v_mov_b32_e32 v94, v0
	v_mov_b32_e32 v95, v0
	v_mov_b32_e32 v104, v0
	v_mov_b32_e32 v105, v0
	v_mov_b32_e32 v106, v0
	v_mov_b32_e32 v107, v0
	v_mov_b32_e32 v108, v0
	v_mov_b32_e32 v109, v0
	v_mov_b32_e32 v110, v0
	v_mov_b32_e32 v111, v0
	v_mov_b32_e32 v120, v0
	v_mov_b32_e32 v121, v0
	v_mov_b32_e32 v122, v0
	v_mov_b32_e32 v123, v0
	v_mov_b32_e32 v124, v0
	v_mov_b32_e32 v125, v0
	v_mov_b32_e32 v126, v0
	v_mov_b32_e32 v127, v0
	s_cmp_eq_u32 s38, 1
	s_cselect_b32 s101, 0x7fffffff, -2
.LBB0_1239:
	ds_read_b128 v[144:147], v151
	ds_read_b128 v[156:159], v151 offset:1024
	ds_read_b128 v[160:163], v151 offset:2048
	ds_read_b128 v[164:167], v151 offset:3072
	ds_read_b128 v[168:171], v152
	ds_read_b128 v[172:175], v152 offset:1024
	ds_read_b128 v[176:179], v152 offset:2048
	ds_read_b128 v[180:183], v152 offset:3072
	s_add_u32 s20, s18, 0xfff50080
	s_addc_u32 s21, s19, -1
	s_cmp_eq_u32 s44, 40
	s_cselect_b32 s23, s5, s21
	s_cselect_b32 s22, s4, s20
	s_cselect_b32 s21, s17, s43
	s_cselect_b32 s20, s16, s42
	v_lshl_add_u64 v[218:219], s[18:19], 0, v[136:137]
	s_add_i32 m0, s25, 0xc000
	ds_read_b128 v[184:187], v153
	ds_read_b128 v[188:191], v153 offset:1024
	ds_read_b128 v[192:195], v153 offset:2048
	ds_read_b128 v[198:201], v153 offset:3072
	ds_read_b128 v[202:205], v153 offset:4096
	ds_read_b128 v[206:209], v153 offset:5120
	ds_read_b128 v[210:213], v153 offset:6144
	ds_read_b128 v[214:217], v153 offset:7168
	global_load_lds_dwordx4 v[218:219], off
	v_lshl_add_u64 v[218:219], s[18:19], 0, v[138:139]
	s_add_i32 m0, s25, 0xe000
	s_nop 0
	global_load_lds_dwordx4 v[218:219], off
	s_cmp_eq_u32 s44, s101
	s_cbranch_scc1 .Lrw4_r0
	s_waitcnt vmcnt(8)
; #define PG8_STAGE(bufoff, gbase, voff) do { _Pragma("unroll") for (int _i = 0; _i < 2; ++_i) \
;         __builtin_amdgcn_global_load_lds((const unsigned*)((const char*)(gbase) + (voff)[_i]), (PG8_LAS unsigned*)(lds + (bufoff) + ldsw + _i * 8192), 16, 0, 0); } while (0)
; #define PG8_LDA(dst, b, h) do { _Pragma("unroll") for (int m = 0; m < 4; ++m) _Pragma("unroll") for (int k = 0; k < 2; ++k) dst[m][k] = *(const PG8_LAS bf16x8*)(lds + PG8_SA(b, h) + aoff + m * 2048 + k * 1024); } while (0)
; #define PG8_MMA(ai, bj, At, Bt) do { __builtin_amdgcn_s_setprio(1); _Pragma("unroll") for (int m = 0; m < 4; ++m) _Pragma("unroll") for (int n = 0; n < 2; ++n) _Pragma("unroll") for (int k = 0; k < 2; ++k) \
;         acc[ai][bj][m][n] = __builtin_amdgcn_mfma_f32_16x16x32_bf16(Bt[n][k], At[m][k], acc[ai][bj][m][n], 0, 0, 0); __builtin_amdgcn_s_setprio(0); } while (0)
; #define PG8_WAIT_V(n) asm volatile("s_waitcnt vmcnt(" #n ")" ::: "memory")
; #define PG8_WAIT_L(n) asm volatile("s_waitcnt lgkmcnt(" #n ")" ::: "memory")
; #define PG8_BAR __builtin_amdgcn_s_barrier()
; #define PG8_SCHED __builtin_amdgcn_sched_barrier(0)
; template <class Epi, class Sched, bool ALIGN_EPI = false, bool SP2 = false>
; __device__ __forceinline__ void gemm_phase(PG8_LAS unsigned char* lds, const Gemm g, const Sched& S, const Epi& E) {
;     ...
;             PG8_WAIT_V(8); PG8_WAIT_L(0); PG8_BAR; PG8_MMA(0, 0, At, B0); PG8_MMA(0, 1, At, B1); PG8_BAR; PG8_SCHED;
;             PG8_LDA(At, 0, 1); PG8_STAGE(PG8_SB(0, 0), b2, voffB); PG8_STAGE(PG8_SB(0, 1), b2 + hstep, voffB); PG8_STAGE(PG8_SA(0, 0), a2, voffA);
;             PG8_WAIT_V(8); PG8_WAIT_L(0); PG8_BAR; PG8_MMA(1, 0, At, B0); PG8_MMA(1, 1, At, B1); PG8_BAR; PG8_SCHED;
.Lrw4_b0:
	s_waitcnt lgkmcnt(0)
	s_barrier
	s_setprio 1
	s_waitcnt lgkmcnt(0)
	v_mfma_f32_16x16x32_bf16 v[124:127], v[144:147], v[184:187], v[124:127]
	v_mfma_f32_16x16x32_bf16 v[120:123], v[160:163], v[184:187], v[120:123]
	v_mfma_f32_16x16x32_bf16 v[108:111], v[144:147], v[192:195], v[108:111]
	v_mfma_f32_16x16x32_bf16 v[104:107], v[160:163], v[192:195], v[104:107]
	v_mfma_f32_16x16x32_bf16 v[92:95], v[144:147], v[202:205], v[92:95]
	v_mfma_f32_16x16x32_bf16 v[88:91], v[160:163], v[202:205], v[88:91]
	v_mfma_f32_16x16x32_bf16 v[76:79], v[144:147], v[210:213], v[76:79]
	v_mfma_f32_16x16x32_bf16 v[72:75], v[160:163], v[210:213], v[72:75]
	v_mfma_f32_16x16x32_bf16 v[124:127], v[156:159], v[188:191], v[124:127]
	v_mfma_f32_16x16x32_bf16 v[120:123], v[164:167], v[188:191], v[120:123]
	v_mfma_f32_16x16x32_bf16 v[108:111], v[156:159], v[198:201], v[108:111]
	v_mfma_f32_16x16x32_bf16 v[104:107], v[164:167], v[198:201], v[104:107]
	v_mfma_f32_16x16x32_bf16 v[92:95], v[156:159], v[206:209], v[92:95]
	v_mfma_f32_16x16x32_bf16 v[88:91], v[164:167], v[206:209], v[88:91]
	v_mfma_f32_16x16x32_bf16 v[76:79], v[156:159], v[214:217], v[76:79]
	v_mfma_f32_16x16x32_bf16 v[72:75], v[164:167], v[214:217], v[72:75]
	s_setprio 0
	s_setprio 1
	v_mfma_f32_16x16x32_bf16 v[116:119], v[168:171], v[184:187], v[116:119]
	v_mfma_f32_16x16x32_bf16 v[112:115], v[176:179], v[184:187], v[112:115]
	v_mfma_f32_16x16x32_bf16 v[100:103], v[168:171], v[192:195], v[100:103]
	v_mfma_f32_16x16x32_bf16 v[96:99], v[176:179], v[192:195], v[96:99]
	v_mfma_f32_16x16x32_bf16 v[84:87], v[168:171], v[202:205], v[84:87]
	v_mfma_f32_16x16x32_bf16 v[80:83], v[176:179], v[202:205], v[80:83]
	v_mfma_f32_16x16x32_bf16 v[68:71], v[168:171], v[210:213], v[68:71]
	v_mfma_f32_16x16x32_bf16 v[64:67], v[176:179], v[210:213], v[64:67]
	v_mfma_f32_16x16x32_bf16 v[116:119], v[172:175], v[188:191], v[116:119]
	v_mfma_f32_16x16x32_bf16 v[112:115], v[180:183], v[188:191], v[112:115]
	v_mfma_f32_16x16x32_bf16 v[100:103], v[172:175], v[198:201], v[100:103]
	v_mfma_f32_16x16x32_bf16 v[96:99], v[180:183], v[198:201], v[96:99]
	v_mfma_f32_16x16x32_bf16 v[84:87], v[172:175], v[206:209], v[84:87]
	v_mfma_f32_16x16x32_bf16 v[80:83], v[180:183], v[206:209], v[80:83]
	v_mfma_f32_16x16x32_bf16 v[68:71], v[172:175], v[214:217], v[68:71]
	v_mfma_f32_16x16x32_bf16 v[64:67], v[180:183], v[214:217], v[64:67]
	s_setprio 0
	s_barrier
	s_add_i32 s45, s36, s24
	v_lshl_add_u64 v[218:219], s[20:21], 0, v[130:131]
	s_mov_b32 m0, s45
	ds_read_b128 v[184:187], v153 offset:16384
	ds_read_b128 v[188:191], v153 offset:17408
	ds_read_b128 v[192:195], v153 offset:18432
	ds_read_b128 v[198:201], v153 offset:19456
	ds_read_b128 v[202:205], v153 offset:20480
	ds_read_b128 v[206:209], v153 offset:21504
	ds_read_b128 v[210:213], v153 offset:22528
	ds_read_b128 v[214:217], v153 offset:23552
	global_load_lds_dwordx4 v[218:219], off
	s_add_i32 m0, s45, 0x2000
	s_add_u32 s46, s20, 0xb0000
	v_lshl_add_u64 v[220:221], s[20:21], 0, v[134:135]
	s_addc_u32 s47, s21, 0
	s_add_i32 s45, s37, s24
	global_load_lds_dwordx4 v[220:221], off
	v_lshl_add_u64 v[222:223], s[46:47], 0, v[130:131]
	s_mov_b32 m0, s45
	v_lshl_add_u64 v[224:225], s[22:23], 0, v[132:133]
	global_load_lds_dwordx4 v[222:223], off
	v_lshl_add_u64 v[222:223], s[46:47], 0, v[134:135]
	s_add_i32 m0, s45, 0x2000
	s_nop 0
	global_load_lds_dwordx4 v[222:223], off
	v_lshl_add_u64 v[222:223], s[22:23], 0, v[128:129]
	s_mov_b32 m0, s25
	s_nop 0
	global_load_lds_dwordx4 v[222:223], off
	s_mov_b32 m0, s26
	s_nop 0
	global_load_lds_dwordx4 v[224:225], off
	s_cmp_eq_u32 s44, s101
	s_cbranch_scc1 .Lrw4_r1
	s_waitcnt vmcnt(8)
.Lrw4_b1:
	s_waitcnt lgkmcnt(0)
	s_barrier
	s_setprio 1
	s_waitcnt lgkmcnt(0)
	v_mfma_f32_16x16x32_bf16 v[60:63], v[144:147], v[184:187], v[60:63]
	v_mfma_f32_16x16x32_bf16 v[56:59], v[160:163], v[184:187], v[56:59]
	v_mfma_f32_16x16x32_bf16 v[44:47], v[144:147], v[192:195], v[44:47]
	v_mfma_f32_16x16x32_bf16 v[40:43], v[160:163], v[192:195], v[40:43]
	v_mfma_f32_16x16x32_bf16 v[28:31], v[144:147], v[202:205], v[28:31]
	v_mfma_f32_16x16x32_bf16 v[24:27], v[160:163], v[202:205], v[24:27]
	v_mfma_f32_16x16x32_bf16 v[12:15], v[144:147], v[210:213], v[12:15]
	v_mfma_f32_16x16x32_bf16 v[8:11], v[160:163], v[210:213], v[8:11]
	v_mfma_f32_16x16x32_bf16 v[60:63], v[156:159], v[188:191], v[60:63]
	v_mfma_f32_16x16x32_bf16 v[56:59], v[164:167], v[188:191], v[56:59]
	v_mfma_f32_16x16x32_bf16 v[44:47], v[156:159], v[198:201], v[44:47]
	v_mfma_f32_16x16x32_bf16 v[40:43], v[164:167], v[198:201], v[40:43]
	v_mfma_f32_16x16x32_bf16 v[28:31], v[156:159], v[206:209], v[28:31]
	v_mfma_f32_16x16x32_bf16 v[24:27], v[164:167], v[206:209], v[24:27]
	v_mfma_f32_16x16x32_bf16 v[12:15], v[156:159], v[214:217], v[12:15]
	v_mfma_f32_16x16x32_bf16 v[8:11], v[164:167], v[214:217], v[8:11]
	s_setprio 0
	s_setprio 1
	v_mfma_f32_16x16x32_bf16 v[52:55], v[168:171], v[184:187], v[52:55]
	v_mfma_f32_16x16x32_bf16 v[48:51], v[176:179], v[184:187], v[48:51]
	v_mfma_f32_16x16x32_bf16 v[36:39], v[168:171], v[192:195], v[36:39]
	v_mfma_f32_16x16x32_bf16 v[32:35], v[176:179], v[192:195], v[32:35]
	v_mfma_f32_16x16x32_bf16 v[20:23], v[168:171], v[202:205], v[20:23]
	v_mfma_f32_16x16x32_bf16 v[16:19], v[176:179], v[202:205], v[16:19]
	v_mfma_f32_16x16x32_bf16 v[4:7], v[168:171], v[210:213], v[4:7]
	v_mfma_f32_16x16x32_bf16 v[0:3], v[176:179], v[210:213], v[0:3]
	v_mfma_f32_16x16x32_bf16 v[52:55], v[172:175], v[188:191], v[52:55]
	v_mfma_f32_16x16x32_bf16 v[48:51], v[180:183], v[188:191], v[48:51]
	v_mfma_f32_16x16x32_bf16 v[36:39], v[172:175], v[198:201], v[36:39]
	v_mfma_f32_16x16x32_bf16 v[32:35], v[180:183], v[198:201], v[32:35]
	v_mfma_f32_16x16x32_bf16 v[20:23], v[172:175], v[206:209], v[20:23]
	v_mfma_f32_16x16x32_bf16 v[16:19], v[180:183], v[206:209], v[16:19]
	v_mfma_f32_16x16x32_bf16 v[4:7], v[172:175], v[214:217], v[4:7]
	v_mfma_f32_16x16x32_bf16 v[0:3], v[180:183], v[214:217], v[0:3]
	s_setprio 0
	s_barrier
; #define PG8_STAGE(bufoff, gbase, voff) do { _Pragma("unroll") for (int _i = 0; _i < 2; ++_i) \
;         __builtin_amdgcn_global_load_lds((const unsigned*)((const char*)(gbase) + (voff)[_i]), (PG8_LAS unsigned*)(lds + (bufoff) + ldsw + _i * 8192), 16, 0, 0); } while (0)
; #define PG8_LDA(dst, b, h) do { _Pragma("unroll") for (int m = 0; m < 4; ++m) _Pragma("unroll") for (int k = 0; k < 2; ++k) dst[m][k] = *(const PG8_LAS bf16x8*)(lds + PG8_SA(b, h) + aoff + m * 2048 + k * 1024); } while (0)
; #define PG8_LDB(dst, b, h) do { _Pragma("unroll") for (int n = 0; n < 2; ++n) _Pragma("unroll") for (int k = 0; k < 2; ++k) dst[n][k] = *(const PG8_LAS bf16x8*)(lds + PG8_SB(b, h) + boff + n * 2048 + k * 1024); } while (0)
; #define PG8_MMA(ai, bj, At, Bt) do { __builtin_amdgcn_s_setprio(1); _Pragma("unroll") for (int m = 0; m < 4; ++m) _Pragma("unroll") for (int n = 0; n < 2; ++n) _Pragma("unroll") for (int k = 0; k < 2; ++k) \
;         acc[ai][bj][m][n] = __builtin_amdgcn_mfma_f32_16x16x32_bf16(Bt[n][k], At[m][k], acc[ai][bj][m][n], 0, 0, 0); __builtin_amdgcn_s_setprio(0); } while (0)
; #define PG8_WAIT_V(n) asm volatile("s_waitcnt vmcnt(" #n ")" ::: "memory")
; #define PG8_WAIT_L(n) asm volatile("s_waitcnt lgkmcnt(" #n ")" ::: "memory")
; #define PG8_BAR __builtin_amdgcn_s_barrier()
; #define PG8_SCHED __builtin_amdgcn_sched_barrier(0)
; template <class Epi, class Sched, bool ALIGN_EPI = false, bool SP2 = false>
; __device__ __forceinline__ void gemm_phase(PG8_LAS unsigned char* lds, const Gemm g, const Sched& S, const Epi& E) {
;     ...
;             PG8_LDB(B0, 1, 0); PG8_LDB(B1, 1, 1); PG8_SCHED; PG8_LDA(At, 1, 0); PG8_STAGE(PG8_SA(0, 1), a2 + hstep, voffA);
;             PG8_WAIT_V(8); PG8_WAIT_L(0); PG8_BAR; PG8_MMA(0, 0, At, B0); PG8_MMA(0, 1, At, B1); PG8_BAR; PG8_SCHED;
	s_add_i32 s45, 0, 0x18000
	v_add_u32_e32 v155, s45, v149
	s_add_i32 s46, 0, 0x1c000
	ds_read_b128 v[144:147], v155
	ds_read_b128 v[156:159], v155 offset:1024
	ds_read_b128 v[160:163], v155 offset:2048
	ds_read_b128 v[164:167], v155 offset:3072
	v_add_u32_e32 v155, s46, v149
	ds_read_b128 v[168:171], v155
	ds_read_b128 v[172:175], v155 offset:1024
	ds_read_b128 v[176:179], v155 offset:2048
	ds_read_b128 v[180:183], v155 offset:3072
	s_add_u32 s22, s22, 0xb0000
	s_addc_u32 s23, s23, 0
	s_mov_b32 m0, s27
	v_lshl_add_u64 v[226:227], s[22:23], 0, v[128:129]
	ds_read_b128 v[184:187], v153 offset:32768
	ds_read_b128 v[188:191], v153 offset:33792
	ds_read_b128 v[192:195], v153 offset:34816
	ds_read_b128 v[198:201], v153 offset:35840
	ds_read_b128 v[202:205], v153 offset:36864
	ds_read_b128 v[206:209], v153 offset:37888
	ds_read_b128 v[210:213], v153 offset:38912
	ds_read_b128 v[214:217], v153 offset:39936
	global_load_lds_dwordx4 v[226:227], off
	v_lshl_add_u64 v[226:227], s[22:23], 0, v[132:133]
	s_mov_b32 m0, s28
	s_nop 0
	global_load_lds_dwordx4 v[226:227], off
	s_waitcnt vmcnt(8)
	s_waitcnt lgkmcnt(0)
	s_barrier
	s_setprio 1
	s_waitcnt lgkmcnt(0)
	v_mfma_f32_16x16x32_bf16 v[124:127], v[144:147], v[184:187], v[124:127]
	v_mfma_f32_16x16x32_bf16 v[120:123], v[160:163], v[184:187], v[120:123]
	v_mfma_f32_16x16x32_bf16 v[108:111], v[144:147], v[192:195], v[108:111]
	v_mfma_f32_16x16x32_bf16 v[104:107], v[160:163], v[192:195], v[104:107]
	v_mfma_f32_16x16x32_bf16 v[92:95], v[144:147], v[202:205], v[92:95]
	v_mfma_f32_16x16x32_bf16 v[88:91], v[160:163], v[202:205], v[88:91]
	v_mfma_f32_16x16x32_bf16 v[76:79], v[144:147], v[210:213], v[76:79]
	v_mfma_f32_16x16x32_bf16 v[72:75], v[160:163], v[210:213], v[72:75]
	v_mfma_f32_16x16x32_bf16 v[124:127], v[156:159], v[188:191], v[124:127]
	v_mfma_f32_16x16x32_bf16 v[120:123], v[164:167], v[188:191], v[120:123]
	v_mfma_f32_16x16x32_bf16 v[108:111], v[156:159], v[198:201], v[108:111]
	v_mfma_f32_16x16x32_bf16 v[104:107], v[164:167], v[198:201], v[104:107]
	v_mfma_f32_16x16x32_bf16 v[92:95], v[156:159], v[206:209], v[92:95]
	v_mfma_f32_16x16x32_bf16 v[88:91], v[164:167], v[206:209], v[88:91]
	v_mfma_f32_16x16x32_bf16 v[76:79], v[156:159], v[214:217], v[76:79]
	v_mfma_f32_16x16x32_bf16 v[72:75], v[164:167], v[214:217], v[72:75]
	s_setprio 0
	s_setprio 1
	v_mfma_f32_16x16x32_bf16 v[116:119], v[168:171], v[184:187], v[116:119]
	v_mfma_f32_16x16x32_bf16 v[112:115], v[176:179], v[184:187], v[112:115]
	v_mfma_f32_16x16x32_bf16 v[100:103], v[168:171], v[192:195], v[100:103]
	v_mfma_f32_16x16x32_bf16 v[96:99], v[176:179], v[192:195], v[96:99]
	v_mfma_f32_16x16x32_bf16 v[84:87], v[168:171], v[202:205], v[84:87]
	v_mfma_f32_16x16x32_bf16 v[80:83], v[176:179], v[202:205], v[80:83]
	v_mfma_f32_16x16x32_bf16 v[68:71], v[168:171], v[210:213], v[68:71]
	v_mfma_f32_16x16x32_bf16 v[64:67], v[176:179], v[210:213], v[64:67]
	v_mfma_f32_16x16x32_bf16 v[116:119], v[172:175], v[188:191], v[116:119]
	v_mfma_f32_16x16x32_bf16 v[112:115], v[180:183], v[188:191], v[112:115]
	v_mfma_f32_16x16x32_bf16 v[100:103], v[172:175], v[198:201], v[100:103]
	v_mfma_f32_16x16x32_bf16 v[96:99], v[180:183], v[198:201], v[96:99]
	v_mfma_f32_16x16x32_bf16 v[84:87], v[172:175], v[206:209], v[84:87]
	v_mfma_f32_16x16x32_bf16 v[80:83], v[180:183], v[206:209], v[80:83]
	v_mfma_f32_16x16x32_bf16 v[68:71], v[172:175], v[214:217], v[68:71]
	v_mfma_f32_16x16x32_bf16 v[64:67], v[180:183], v[214:217], v[64:67]
	s_setprio 0
	s_barrier
; #define PG8_STAGE(bufoff, gbase, voff) do { _Pragma("unroll") for (int _i = 0; _i < 2; ++_i) \
;         __builtin_amdgcn_global_load_lds((const unsigned*)((const char*)(gbase) + (voff)[_i]), (PG8_LAS unsigned*)(lds + (bufoff) + ldsw + _i * 8192), 16, 0, 0); } while (0)
; #define PG8_LDA(dst, b, h) do { _Pragma("unroll") for (int m = 0; m < 4; ++m) _Pragma("unroll") for (int k = 0; k < 2; ++k) dst[m][k] = *(const PG8_LAS bf16x8*)(lds + PG8_SA(b, h) + aoff + m * 2048 + k * 1024); } while (0)
; #define PG8_MMA(ai, bj, At, Bt) do { __builtin_amdgcn_s_setprio(1); _Pragma("unroll") for (int m = 0; m < 4; ++m) _Pragma("unroll") for (int n = 0; n < 2; ++n) _Pragma("unroll") for (int k = 0; k < 2; ++k) \
;         acc[ai][bj][m][n] = __builtin_amdgcn_mfma_f32_16x16x32_bf16(Bt[n][k], At[m][k], acc[ai][bj][m][n], 0, 0, 0); __builtin_amdgcn_s_setprio(0); } while (0)
; #define PG8_WAIT_V(n) asm volatile("s_waitcnt vmcnt(" #n ")" ::: "memory")
; #define PG8_WAIT_L(n) asm volatile("s_waitcnt lgkmcnt(" #n ")" ::: "memory")
; #define PG8_BAR __builtin_amdgcn_s_barrier()
; #define PG8_SCHED __builtin_amdgcn_sched_barrier(0)
; template <class Epi, class Sched, bool ALIGN_EPI = false, bool SP2 = false>
; __device__ __forceinline__ void gemm_phase(PG8_LAS unsigned char* lds, const Gemm g, const Sched& S, const Epi& E) {
;     ...
;             PG8_LDA(At, 1, 1); PG8_STAGE(PG8_SB(1, 0), b3, voffB); PG8_STAGE(PG8_SB(1, 1), b3 + hstep, voffB); PG8_STAGE(PG8_SA(1, 0), a3, voffA);
;             PG8_WAIT_V(8); PG8_WAIT_L(0); PG8_BAR; PG8_MMA(1, 0, At, B0); PG8_MMA(1, 1, At, B1); PG8_BAR; PG8_SCHED;
	s_add_i32 s22, s45, s24
	v_lshl_add_u64 v[218:219], v[218:219], 0, s[12:13]
	s_mov_b32 m0, s22
	ds_read_b128 v[184:187], v153 offset:49152
	ds_read_b128 v[188:191], v153 offset:50176
	ds_read_b128 v[192:195], v153 offset:51200
	ds_read_b128 v[198:201], v153 offset:52224
	ds_read_b128 v[202:205], v153 offset:53248
	ds_read_b128 v[206:209], v153 offset:54272
	ds_read_b128 v[210:213], v153 offset:55296
	ds_read_b128 v[214:217], v153 offset:56320
	global_load_lds_dwordx4 v[218:219], off
	s_add_i32 m0, s22, 0x2000
	s_add_u32 s20, s20, 0xb0080
	v_lshl_add_u64 v[218:219], v[220:221], 0, s[12:13]
	s_addc_u32 s21, s21, 0
	s_add_i32 s22, s46, s24
	global_load_lds_dwordx4 v[218:219], off
	v_lshl_add_u64 v[218:219], s[20:21], 0, v[130:131]
	s_mov_b32 m0, s22
	s_nop 0
	global_load_lds_dwordx4 v[218:219], off
	v_lshl_add_u64 v[218:219], s[20:21], 0, v[134:135]
	s_add_i32 m0, s22, 0x2000
	s_nop 0
	global_load_lds_dwordx4 v[218:219], off
	v_lshl_add_u64 v[218:219], v[222:223], 0, s[12:13]
	s_mov_b32 m0, s33
	s_nop 0
	global_load_lds_dwordx4 v[218:219], off
	v_lshl_add_u64 v[218:219], v[224:225], 0, s[12:13]
	s_mov_b32 m0, s34
	s_nop 0
	global_load_lds_dwordx4 v[218:219], off
	s_waitcnt vmcnt(8)
	s_waitcnt lgkmcnt(0)
	s_barrier
	s_setprio 1
	s_waitcnt lgkmcnt(0)
	v_mfma_f32_16x16x32_bf16 v[60:63], v[144:147], v[184:187], v[60:63]
	v_mfma_f32_16x16x32_bf16 v[56:59], v[160:163], v[184:187], v[56:59]
	v_mfma_f32_16x16x32_bf16 v[44:47], v[144:147], v[192:195], v[44:47]
	v_mfma_f32_16x16x32_bf16 v[40:43], v[160:163], v[192:195], v[40:43]
	v_mfma_f32_16x16x32_bf16 v[28:31], v[144:147], v[202:205], v[28:31]
	v_mfma_f32_16x16x32_bf16 v[24:27], v[160:163], v[202:205], v[24:27]
	v_mfma_f32_16x16x32_bf16 v[12:15], v[144:147], v[210:213], v[12:15]
	v_mfma_f32_16x16x32_bf16 v[8:11], v[160:163], v[210:213], v[8:11]
	v_mfma_f32_16x16x32_bf16 v[60:63], v[156:159], v[188:191], v[60:63]
	v_mfma_f32_16x16x32_bf16 v[56:59], v[164:167], v[188:191], v[56:59]
	v_mfma_f32_16x16x32_bf16 v[44:47], v[156:159], v[198:201], v[44:47]
	v_mfma_f32_16x16x32_bf16 v[40:43], v[164:167], v[198:201], v[40:43]
	v_mfma_f32_16x16x32_bf16 v[28:31], v[156:159], v[206:209], v[28:31]
	v_mfma_f32_16x16x32_bf16 v[24:27], v[164:167], v[206:209], v[24:27]
	v_mfma_f32_16x16x32_bf16 v[12:15], v[156:159], v[214:217], v[12:15]
	v_mfma_f32_16x16x32_bf16 v[8:11], v[164:167], v[214:217], v[8:11]
	s_setprio 0
	s_setprio 1
	v_mfma_f32_16x16x32_bf16 v[52:55], v[168:171], v[184:187], v[52:55]
	v_mfma_f32_16x16x32_bf16 v[48:51], v[176:179], v[184:187], v[48:51]
	v_mfma_f32_16x16x32_bf16 v[36:39], v[168:171], v[192:195], v[36:39]
	v_mfma_f32_16x16x32_bf16 v[32:35], v[176:179], v[192:195], v[32:35]
	v_mfma_f32_16x16x32_bf16 v[20:23], v[168:171], v[202:205], v[20:23]
	v_mfma_f32_16x16x32_bf16 v[16:19], v[176:179], v[202:205], v[16:19]
	v_mfma_f32_16x16x32_bf16 v[4:7], v[168:171], v[210:213], v[4:7]
	v_mfma_f32_16x16x32_bf16 v[0:3], v[176:179], v[210:213], v[0:3]
	v_mfma_f32_16x16x32_bf16 v[52:55], v[172:175], v[188:191], v[52:55]
	v_mfma_f32_16x16x32_bf16 v[48:51], v[180:183], v[188:191], v[48:51]
	v_mfma_f32_16x16x32_bf16 v[36:39], v[172:175], v[198:201], v[36:39]
	v_mfma_f32_16x16x32_bf16 v[32:35], v[180:183], v[198:201], v[32:35]
	v_mfma_f32_16x16x32_bf16 v[20:23], v[172:175], v[206:209], v[20:23]
	v_mfma_f32_16x16x32_bf16 v[16:19], v[180:183], v[206:209], v[16:19]
	v_mfma_f32_16x16x32_bf16 v[4:7], v[172:175], v[214:217], v[4:7]
	v_mfma_f32_16x16x32_bf16 v[0:3], v[180:183], v[214:217], v[0:3]
	s_setprio 0
	s_barrier
	s_add_i32 s44, s44, 2
	s_add_u32 s18, s18, 0x100
	s_addc_u32 s19, s19, 0
	s_add_u32 s42, s42, 0x100
	s_addc_u32 s43, s43, 0
	s_cmp_gt_u32 s44, 41
	s_cbranch_scc0 .LBB0_1239
	s_branch .Lrw4_x

; __device__ __forceinline__ unsigned cvt_pk_bf16(float lo, float hi) { unsigned r; asm volatile("v_cvt_pk_bf16_f32 %0, %1, %2" : "=v"(r) : "v"(lo), "v"(hi)); return r; }
; #define PG8_BAR __builtin_amdgcn_s_barrier()
;     __device__ __forceinline__ void operator()(const f32x4 (&acc)[2][2][4][2], const Unit& u, int wr, int wc, int fr, int fq) const {
;         const int row0 = u.pm * BM + wr * 64 + fr, col0 = u.pn * BM + wc * 32 + 8 * fq;
; #pragma unroll
;         for (int ai = 0; ai < 2; ++ai)
; #pragma unroll
;             for (int m = 0; m < 4; ++m) {
;                 const int row = row0 + ai * HALF + m * 16; float s = 0.f;
; #pragma unroll
;                 for (int bj = 0; bj < 2; ++bj) {
;                     const f32x4 v0 = acc[ai][bj][m][0], v1 = acc[ai][bj][m][1];
;                     s += (v0[0] * v0[0] + v0[1] * v0[1]) + (v0[2] * v0[2] + v0[3] * v0[3]) + (v1[0] * v1[0] + v1[1] * v1[1]) + (v1[2] * v1[2] + v1[3] * v1[3]);
;                     u32x4 w; w.x = cvt_pk_bf16(v0[0], v0[1]); w.y = cvt_pk_bf16(v0[2], v0[3]); w.z = cvt_pk_bf16(v1[0], v1[1]); w.w = cvt_pk_bf16(v1[2], v1[3]);
;                     *(u32x4*)(O + (size_t)row * 1024 + col0 + bj * HALF) = w;
;                 }
;                 s += __shfl_xor(s, 16); s += __shfl_xor(s, 32);
;                 if (fq == 0) rsq[(size_t)row * 16 + u.pn * 4 + wc] = s;
; template <class Epi, class Sched, bool ALIGN_EPI = false, bool SP2 = false>
; __device__ __forceinline__ void gemm_phase(PG8_LAS unsigned char* lds, const Gemm g, const Sched& S, const Epi& E) {
;     ...
;         if constexpr (ALIGN_EPI) { if (wr == 0) PG8_BAR; }
.Lrw4_x:
	s_and_b64 vcc, exec, s[14:15]
	s_cbranch_vccz .LBB0_1242
	s_barrier
.LBB0_1242:
	v_mul_f32_e32 v155, v125, v125
	v_mul_f32_e32 v158, v127, v127
	v_fmac_f32_e32 v155, v124, v124
	v_fmac_f32_e32 v158, v126, v126
	v_add_f32_e32 v155, v155, v158
	v_mul_f32_e32 v158, v121, v121
	v_fmac_f32_e32 v158, v120, v120
	v_cvt_pk_bf16_f32 v124, v124, v125
	v_cvt_pk_bf16_f32 v125, v126, v127
	v_cvt_pk_bf16_f32 v126, v120, v121
	v_mul_f32_e32 v120, v117, v117
	v_mul_f32_e32 v121, v119, v119
	v_fmac_f32_e32 v120, v116, v116
	v_fmac_f32_e32 v121, v118, v118
	v_add_f32_e32 v120, v120, v121
	v_mul_f32_e32 v121, v113, v113
	v_fmac_f32_e32 v121, v112, v112
	v_add_f32_e32 v155, v155, v158
	v_mul_f32_e32 v158, v123, v123
	v_add_f32_e32 v120, v120, v121
	v_mul_f32_e32 v121, v115, v115
	v_fmac_f32_e32 v158, v122, v122
	v_fmac_f32_e32 v121, v114, v114
	v_add_f32_e32 v155, v158, v155
	v_cvt_pk_bf16_f32 v127, v122, v123
	v_add_f32_e32 v120, v121, v120
	v_and_b32_e32 v122, 64, v154
	v_add_f32_e32 v121, v155, v120
	v_xor_b32_e32 v120, 16, v154
	v_add_u32_e32 v155, 64, v122
	v_lshl_add_u32 v146, s41, 8, v148
	v_cmp_lt_i32_e32 vcc, v120, v155
	v_ashrrev_i32_e32 v147, 31, v146
	v_lshl_or_b32 v144, s8, 8, v150
	v_cndmask_b32_e32 v120, v154, v120, vcc
	v_lshlrev_b64 v[156:157], 11, v[146:147]
	v_lshlrev_b32_e32 v120, 2, v120
	v_ashrrev_i32_e32 v145, 31, v144
	ds_bpermute_b32 v158, v120, v121
	v_lshl_add_u64 v[122:123], s[84:85], 0, v[156:157]
	v_lshl_add_u64 v[156:157], v[144:145], 1, v[122:123]
	global_store_dwordx4 v[156:157], v[124:127], off
	v_cvt_pk_bf16_f32 v122, v116, v117
	v_xor_b32_e32 v116, 32, v154
	v_cmp_lt_i32_e32 vcc, v116, v155
	s_waitcnt lgkmcnt(0)
	v_add_f32_e32 v117, v121, v158
	s_lshl_b32 s18, s8, 2
	v_cndmask_b32_e32 v116, v154, v116, vcc
	v_lshlrev_b32_e32 v116, 2, v116
	ds_bpermute_b32 v121, v116, v117
	s_ashr_i32 s19, s18, 31
	v_cvt_pk_bf16_f32 v123, v118, v119
	v_cvt_pk_bf16_f32 v124, v112, v113
	v_cvt_pk_bf16_f32 v125, v114, v115
	global_store_dwordx4 v[156:157], v[122:125], off offset:256
	s_and_saveexec_b64 s[20:21], s[0:1]
	s_cbranch_execz .LBB0_1244
	v_lshlrev_b64 v[112:113], 6, v[146:147]
	v_lshl_add_u64 v[112:113], s[78:79], 0, v[112:113]
	v_lshl_add_u64 v[112:113], s[18:19], 2, v[112:113]
	s_lshl_b32 s8, s31, 2
	s_waitcnt lgkmcnt(0)
	v_add_f32_e32 v114, v117, v121
	v_lshl_add_u64 v[112:113], v[112:113], 0, s[8:9]
	global_store_dword v[112:113], v114, off
